# P0 mod GEMV: 16 weight-row loads in flight per unit (was 4 per trip); mid-file trampolines for the phase-loop branches
# baseline (speedup 1.0000x reference)
;     __device__ __forceinline__ void operator()(const f32x4 (&acc)[2][2][4][2], const Unit& u, int wr, int wc, int fr, int fq) const {
;     ...
;             const int mrow = is_ctx ? 4 : batch; const int col0 = u.pn * BM + wc * 32 + 8 * fq; const int gidx = aux & 15, ll = aux >> 4;
;             const float gs = gidx == 5 ? 1.f : 0.5f; float* f0 = (float*)(ws + WS_H);
;             const float* g = (const float*)(ws + WS_MOD) + (size_t)(ll * 5 + mrow) * NMOD + gidx * DM + col0;
; template <class Epi, class Sched>
; __device__ __forceinline__ void gemm_phase(LAS unsigned char* lds, const Gemm g, const Sched& S, const Epi& E, const int tid) {
;     const int wid = __builtin_amdgcn_readfirstlane(tid >> 6), lane = tid & 63, wr = wid >> 2, wc = wid & 3, fr = lane & 15, fq = lane >> 4;
;     const int K = g.K, nt = g.nt;
;     unsigned voffA[2], voffB[2];
; #pragma unroll
;     for (int i = 0; i < 2; ++i) { int R, C; stage_rc(tid * 16 + i * 8192, R, C); const int Rb = Epi::PERM ? ((R & ~31) + perm32(R & 31)) : R;
;         voffA[i] = (unsigned)(R * K + C) * 2u; voffB[i] = (unsigned)(Rb * K + C) * 2u; }
;     const size_t kstep = (size_t)(BK * 2);
;     const size_t hstep = (size_t)HALF * K * 2;
;     const size_t tstep = 2 * hstep;
;     const unsigned ldsw = (unsigned)wid * 1024u;
;     const int aoff = lds_byte(wr * 64 + fr, fq * 8), boff = lds_byte(wc * 32 + fr, fq * 8);
.LBB0_217:
	v_writelane_b32 v254, s94, 57
	s_andn2_b64 vcc, exec, s[8:9]
	s_nop 0
	v_writelane_b32 v254, s95, 58
	v_writelane_b32 v254, s93, 59
	s_cbranch_vccnz .LBB0_453
	v_bfe_i32 v2, v146, 27, 1
	v_lshlrev_b32_e32 v0, 4, v146
	v_lshrrev_b32_e32 v2, 22, v2
	v_add_u32_e32 v2, v0, v2
	v_and_b32_e32 v2, 0xfffffc00, v2
	v_sub_u32_e32 v2, v0, v2
	s_waitcnt lgkmcnt(0)
	v_lshrrev_b32_e32 v3, 4, v2
	v_ashrrev_i32_e32 v1, 31, v146
	v_bitop3_b32 v2, v3, v2, 32 bitop3:0x6c
	v_lshrrev_b32_e32 v1, 26, v1
	s_waitcnt vmcnt(0)
	v_ashrrev_i32_e32 v4, 31, v2
	s_cmp_eq_u32 s21, 2
	v_add_u32_e32 v1, v146, v1
	v_lshrrev_b32_e32 v4, 26, v4
	s_cselect_b64 s[62:63], -1, 0
	s_lshr_b32 s6, s20, 6
	v_ashrrev_i32_e32 v1, 6, v1
	v_add_u32_e32 v4, v2, v4
	s_cmp_lg_u32 s11, 0
	v_lshlrev_b32_e32 v3, 3, v1
	v_ashrrev_i32_e32 v5, 6, v4
	v_and_b32_e32 v4, 0xc0, v4
	v_writelane_b32 v254, s6, 60
	s_cselect_b64 s[6:7], -1, 0
	v_and_b32_e32 v3, -16, v3
	v_lshlrev_b32_e32 v1, 5, v1
	v_sub_u32_e32 v2, v2, v4
	v_writelane_b32 v254, s6, 61
	v_add_u32_e32 v3, v5, v3
	v_and_b32_e32 v1, 32, v1
	v_ashrrev_i16_sdwa v2, v252, sext(v2) dst_sel:DWORD dst_unused:UNUSED_PAD src0_sel:DWORD src1_sel:BYTE_0
	v_writelane_b32 v254, s7, 62
	v_add_u32_sdwa v1, v1, sext(v2) dst_sel:DWORD dst_unused:UNUSED_PAD src0_sel:DWORD src1_sel:WORD_0
	v_lshlrev_b32_e32 v2, 1, v3
	v_lshrrev_b32_e32 v4, 2, v3
	v_and_b32_e32 v5, 3, v5
	s_mov_b32 s6, 0x7fffffe0
	v_and_b32_e32 v2, 24, v2
	v_and_b32_e32 v4, 4, v4
	v_and_or_b32 v5, v3, s6, v5
	v_or3_b32 v2, v5, v4, v2
	v_mul_lo_u32 v3, s20, v3
	v_mul_lo_u32 v2, s20, v2
	v_add_u32_e32 v0, 0x2000, v0
	v_add_lshl_u32 v150, v3, v1, 1
	v_add_lshl_u32 v152, v2, v1, 1
	v_ashrrev_i32_e32 v1, 31, v0
	v_lshrrev_b32_e32 v1, 22, v1
	v_add_u32_e32 v1, v0, v1
	v_ashrrev_i32_e32 v1, 10, v1
	v_mul_i32_i24_e32 v2, 0x400, v1
	v_sub_u32_e32 v0, v0, v2
	v_lshrrev_b32_e32 v2, 4, v0
	v_bitop3_b32 v0, v2, v0, 32 bitop3:0x6c
	v_ashrrev_i32_e32 v3, 31, v0
	v_lshrrev_b32_e32 v3, 26, v3
	v_lshlrev_b32_e32 v2, 3, v1
	v_add_u32_e32 v3, v0, v3
	s_cmp_eq_u32 s11, 0
	v_and_b32_e32 v2, -16, v2
	v_ashrrev_i32_e32 v4, 6, v3
	s_cselect_b32 s14, 0x44, 64
	v_add_u32_e32 v2, v4, v2
	v_and_b32_e32 v4, 3, v4
	s_ashr_i32 s93, s2, 31
	v_and_or_b32 v4, v2, s6, v4
	s_lshr_b32 s6, s93, 29
	s_add_i32 s6, s2, s6
	s_lshl_b32 s24, s20, 8
	s_mov_b32 s25, s37
	s_ashr_i32 s8, s6, 3
	s_and_b32 s6, s6, -8
	s_lshr_b32 s15, s20, 8
	s_lshl_b64 s[26:27], s[24:25], 1
	s_lshr_b32 s22, s20, 4
	s_sub_i32 s9, s2, s6
	s_lshl_b32 s21, s10, 3
	s_add_u32 s6, s0, 0x10369000
	s_addc_u32 s7, s1, 0
	s_add_u32 s30, s0, 0x6c5b000
	v_writelane_b32 v254, s6, 63
	s_addc_u32 s31, s1, 0
	v_readlane_b32 s12, v254, 55
	v_writelane_b32 v255, s7, 0
	s_add_u32 s6, s0, 0xbf69000
	s_addc_u32 s7, s1, 0
	v_writelane_b32 v255, s6, 1
	v_and_b32_e32 v3, 0xc0, v3
	v_readlane_b32 s13, v254, 56
	v_writelane_b32 v255, s7, 2
	s_add_u32 s6, s0, 0xe169000
	s_addc_u32 s7, s1, 0
	v_writelane_b32 v255, s6, 3
	s_and_b32 s11, s3, 15
	s_ashr_i32 s3, s3, 4
	v_writelane_b32 v255, s7, 4
	s_cmp_eq_u32 s11, 5
	s_mul_i32 s3, s3, 5
	s_cselect_b64 s[6:7], -1, 0
	v_writelane_b32 v255, s3, 5
	s_add_i32 s3, s3, 4
	v_cndmask_b32_e64 v158, 0.5, 1.0, s[6:7]
	s_mul_hi_i32 s6, s3, 0x9000
	s_mul_i32 s3, s3, 0x9000
	s_add_u32 s3, s12, s3
	v_lshlrev_b32_e32 v1, 5, v1
	v_sub_u32_e32 v0, v0, v3
	s_addc_u32 s6, s13, s6
	s_lshl_b32 s7, s11, 12
	v_and_b32_e32 v1, 32, v1
	v_ashrrev_i16_sdwa v0, v252, sext(v0) dst_sel:DWORD dst_unused:UNUSED_PAD src0_sel:DWORD src1_sel:BYTE_0
	s_add_u32 s28, s3, s7
	v_add_u32_sdwa v0, v1, sext(v0) dst_sel:DWORD dst_unused:UNUSED_PAD src0_sel:DWORD src1_sel:WORD_0
	v_lshlrev_b32_e32 v1, 1, v2
	v_lshrrev_b32_e32 v3, 2, v2
	s_addc_u32 s29, s6, 0
	v_and_b32_e32 v1, 24, v1
	v_and_b32_e32 v3, 4, v3
	v_writelane_b32 v255, s28, 6
	v_or3_b32 v1, v4, v3, v1
	s_add_u32 s3, s12, s7
	v_writelane_b32 v255, s29, 7
	v_mul_lo_u32 v1, s20, v1
	v_writelane_b32 v255, s3, 8
	s_addc_u32 s3, s13, 0
	v_mul_lo_u32 v2, s20, v2
;     __device__ bool next(int i, Unit& u) const {
;         const long L = (long)i * G + c; if (L >= nwg) return false;
;         if (mode == 2) { const int sp = (int)L % nsplit, t = (int)L / nsplit; u.pn = t & 3; u.pm = 17 * (t >> 2); u.kb = sp * 512; return true; }
;         int wgid = (int)L; { const int q = nwg / NXCD, r = nwg % NXCD, xcd = wgid % NXCD, off = wgid / NXCD; wgid = (xcd < r ? xcd * (q + 1) : r * (q + 1) + (xcd - r) * q) + off; }
;         const int nig = WGM * nN, gid = wgid / nig, fm = gid * WGM, gsz = (nM - fm) < WGM ? (nM - fm) : WGM;
;         u.pm = fm + ((wgid % nig) % gsz); u.pn = (wgid % nig) / gsz; u.kb = 0;
;         if (mode == 1) u.pm = u.pm + u.pm / 16 + 1;
	v_add_lshl_u32 v156, v1, v0, 1
	v_and_b32_e32 v147, 15, v146
	v_bfe_u32 v199, v146, 4, 2
	v_lshlrev_b32_e32 v1, 2, v146
	v_writelane_b32 v255, s3, 9
	s_add_u32 s3, s0, 0x16969000
	v_add_lshl_u32 v154, v2, v0, 1
	v_lshlrev_b32_e32 v200, 4, v199
	v_lshlrev_b32_e32 v0, 6, v147
	v_and_b32_e32 v1, 32, v1
	v_writelane_b32 v255, s3, 10
	s_addc_u32 s3, s1, 0
	s_abs_i32 s92, s15
	v_bitop3_b32 v201, v200, v1, v0 bitop3:0x36
	v_cvt_f32_u32_e32 v0, s92
	s_mul_i32 s20, s14, s10
	v_writelane_b32 v255, s3, 11
	s_lshr_b32 s3, s20, 3
	v_rcp_iflag_f32_e32 v0, v0
	s_lshr_b32 s6, s9, 31
	s_add_i32 s3, s3, s6
	s_mul_i32 s3, s3, s9
	v_mul_f32_e32 v0, 0x4f7ffffe, v0
	v_cvt_u32_f32_e32 v0, v0
	s_add_i32 s3, s3, s8
	s_sub_i32 s8, 0, s92
	s_ashr_i32 s6, s15, 31
	v_readfirstlane_b32 s9, v0
	s_mul_i32 s8, s8, s9
	s_mul_hi_u32 s8, s9, s8
	v_writelane_b32 v255, s6, 12
	s_abs_i32 s7, s2
	s_add_i32 s8, s9, s8
	v_writelane_b32 v255, s8, 13
	s_mul_hi_u32 s8, s7, s8
	s_mul_i32 s9, s8, s92
	s_sub_i32 s7, s7, s9
	s_xor_b32 s6, s93, s6
	s_add_i32 s9, s8, 1
	s_sub_i32 s11, s7, s92
	s_cmp_ge_u32 s7, s92
	s_cselect_b32 s8, s9, s8
	s_cselect_b32 s7, s11, s7
	s_add_i32 s9, s8, 1
	s_cmp_ge_u32 s7, s92
	s_cselect_b32 s7, s9, s8
	s_abs_i32 s82, s21
	v_cvt_f32_u32_e32 v0, s82
	s_xor_b32 s7, s7, s6
	s_sub_i32 s6, s7, s6
	v_writelane_b32 v255, s15, 14
	v_rcp_iflag_f32_e32 v0, v0
	s_mul_i32 s7, s6, s15
	s_and_b32 s8, s6, 3
	s_sub_i32 s7, s2, s7
	v_mul_f32_e32 v0, 0x4f7ffffe, v0
	v_cvt_u32_f32_e32 v0, v0
	v_writelane_b32 v255, s8, 15
	s_bfe_i32 s8, s10, 0x1001c
	s_sub_i32 s9, 0, s82
	v_readfirstlane_b32 s10, v0
	s_lshl_b32 s7, s7, 9
	s_mul_i32 s9, s9, s10
	v_writelane_b32 v255, s7, 16
	s_ashr_i32 s7, s3, 31
	s_mul_hi_u32 s9, s10, s9
	v_writelane_b32 v255, s8, 17
	s_xor_b32 s7, s7, s8
	s_abs_i32 s8, s3
	s_add_i32 s9, s10, s9
	s_mov_b32 s64, s9
	s_mul_hi_u32 s9, s8, s9
	s_mul_i32 s10, s9, s82
	s_sub_i32 s8, s8, s10
	s_ashr_i32 s6, s6, 2
	s_add_i32 s10, s9, 1
	s_sub_i32 s11, s8, s82
	s_cmp_ge_u32 s8, s82
	s_cselect_b32 s9, s10, s9
	s_cselect_b32 s8, s11, s8
	s_add_i32 s10, s9, 1
	s_cmp_ge_u32 s8, s82
	s_cselect_b32 s8, s10, s9
	s_xor_b32 s8, s8, s7
	s_sub_i32 s7, s8, s7
	s_lshl_b32 s8, s7, 3
	s_sub_i32 s9, s14, s8
	s_min_i32 s9, s9, 8
	s_abs_i32 s10, s9
	v_cvt_f32_u32_e32 v0, s10
	s_sub_i32 s11, 0, s10
	s_mul_i32 s7, s7, s21
	s_sub_i32 s3, s3, s7
	v_rcp_iflag_f32_e32 v0, v0
	s_abs_i32 s7, s3
	s_mul_i32 s6, s6, 17
	v_writelane_b32 v255, s6, 18
	v_mul_f32_e32 v0, 0x4f7ffffe, v0
	v_cvt_u32_f32_e32 v0, v0
	s_xor_b32 s6, s3, s9
	s_ashr_i32 s6, s6, 31
	v_mov_b32_e32 v151, v145
	v_readfirstlane_b32 s12, v0
	s_mul_i32 s11, s11, s12
	s_mul_hi_u32 s11, s12, s11
	s_add_i32 s12, s12, s11
	s_mul_hi_u32 s11, s7, s12
	s_mul_i32 s12, s11, s10
	s_sub_i32 s7, s7, s12
	s_add_i32 s12, s11, 1
	s_sub_i32 s13, s7, s10
	s_cmp_ge_u32 s7, s10
	s_cselect_b32 s11, s12, s11
	s_cselect_b32 s7, s13, s7
	s_add_i32 s12, s11, 1
	s_cmp_ge_u32 s7, s10
	s_cselect_b32 s7, s12, s11
	s_xor_b32 s7, s7, s6
	s_sub_i32 s6, s7, s6
	v_writelane_b32 v255, s6, 19
	s_mul_i32 s6, s6, s9
	s_sub_i32 s3, s3, s6
	s_add_i32 s6, s3, s8
	s_ashr_i32 s3, s6, 31
	s_lshr_b32 s3, s3, 28
	s_add_i32 s3, s6, s3
	s_ashr_i32 s3, s3, 4
	s_add_i32 s3, s6, s3
	v_writelane_b32 v255, s6, 20
	s_add_i32 s3, s3, 1
	v_writelane_b32 v255, s3, 21
	v_writelane_b32 v255, s20, 22
	v_writelane_b32 v255, s22, 23
	v_mov_b32_e32 v155, v145
	v_writelane_b32 v255, s62, 24
	v_mov_b32_e32 v153, v145
	v_mov_b32_e32 v157, v145
	s_mov_b32 s66, s14
	v_mov_b32_e32 v160, v158
	v_mov_b32_e32 v161, v158
	s_mov_b32 s65, s21
	v_lshl_add_u64 v[162:163], s[24:25], 0, v[154:155]
	v_lshl_add_u64 v[164:165], s[24:25], 0, v[150:151]
	s_mov_b64 s[46:47], -1
	v_writelane_b32 v255, s63, 25
	s_branch .LBB0_221
.Ltramp_1:
	s_branch .LBB0_1
.Ltramp_2:
	s_branch .LBB0_2
.Ltramp_end:
	s_branch .LBB0_689
.LBB0_219:
	s_waitcnt vmcnt(0)
	v_readlane_b32 s62, v255, 24
	v_readlane_b32 s63, v255, 25
	v_readlane_b32 s20, v255, 22
	v_readlane_b32 s22, v255, 23
	s_barrier

; __global__ void __launch_bounds__(512) mk_fwd(Params P) {
;     ...
;             for (int unit = bid; unit < 1152; unit += G) {
;                 const int ks = unit & 7, cgp = (unit >> 3) % 36, ll = unit / 288;
;                 const float* W = P.in[4] + (size_t)ll * DM * NMOD + cgp * 256 + lane * 4;
;                 const int kbase = ks * 128 + wave * 16;
;                 f32x4 a[5];
; #pragma unroll
;                 for (int r = 0; r < 5; ++r) a[r] = (f32x4){0.f, 0.f, 0.f, 0.f};
; #pragma unroll 4
;                 for (int kk = 0; kk < 16; ++kk) { const int k = kbase + kk; const f32x4 w = __builtin_nontemporal_load((const f32x4*)(W + (size_t)k * NMOD));
; #pragma unroll
;                     for (int r = 0; r < 5; ++r) a[r] += w * cond[r * 1024 + k]; }
; #pragma unroll
;                 for (int r = 0; r < 5; ++r) *(f32x4*)(red + (wave * 5 + r) * 256 + lane * 4) = a[r];
;                 __syncthreads();
;                 for (int o = tid; o < 1280; o += 512) { const int r = o >> 8, cc = o & 255; float sum = 0.f;
; #pragma unroll
;                     for (int w = 0; w < 8; ++w) sum += red[(w * 5 + r) * 256 + cc];
;                     MODP[(size_t)((ks * 4 + ll) * 5 + r) * NMOD + cgp * 256 + cc] = sum; }
.LBB0_597:
	s_and_b32 s0, s10, 7
	s_mul_i32 s6, s0, 0x480000
	s_lshl_b32 s0, s0, 9
	s_add_i32 s12, s3, s0
	s_ashr_i32 s0, s2, 3
	s_mul_hi_i32 s1, s0, 0x38e38e39
	s_lshr_b32 s7, s1, 31
	s_lshr_b32 s1, s1, 3
	s_add_i32 s1, s1, s7
	s_mul_i32 s1, s1, 36
	s_sub_i32 s0, s0, s1
	s_mul_hi_i32 s1, s2, 0x38e38e39
	s_lshr_b32 s7, s1, 31
	s_ashr_i32 s11, s1, 6
	s_add_i32 s11, s11, s7
	s_lshl_b32 s0, s0, 8
	s_mul_i32 s8, s11, 0x2400000
	s_ashr_i32 s1, s0, 31
	s_mul_hi_i32 s7, s11, 0x2400000
	s_add_u32 s8, s8, s6
	s_addc_u32 s9, s7, 0
	s_lshl_b64 s[6:7], s[0:1], 2
	s_add_u32 s6, s8, s6
	s_addc_u32 s7, s9, s7
	v_mov_b32_e32 v0, 0
	v_lshl_add_u64 v[24:25], v[22:23], 0, s[6:7]
	s_mov_b64 s[8:9], 0
	v_mov_b32_e32 v1, v0
	v_mov_b32_e32 v2, v0
	v_mov_b32_e32 v3, v0
	v_mov_b32_e32 v4, v0
	v_mov_b32_e32 v5, v0
	v_mov_b32_e32 v6, v0
	v_mov_b32_e32 v7, v0
	v_mov_b32_e32 v8, v0
	v_mov_b32_e32 v9, v0
	v_mov_b32_e32 v10, v0
	v_mov_b32_e32 v11, v0
	v_mov_b32_e32 v12, v0
	v_mov_b32_e32 v13, v0
	v_mov_b32_e32 v14, v0
	v_mov_b32_e32 v15, v0
	v_mov_b32_e32 v16, v0
	v_mov_b32_e32 v17, v0
	v_mov_b32_e32 v18, v0
	v_mov_b32_e32 v19, v0
	s_mov_b64 s[6:7], 0x0
	v_lshl_add_u64 v[120:121], v[24:25], 0, s[6:7]
	global_load_dwordx4 v[28:31], v[120:121], off nt
	s_mov_b64 s[6:7], 0x9000
	v_lshl_add_u64 v[120:121], v[24:25], 0, s[6:7]
	global_load_dwordx4 v[32:35], v[120:121], off nt
	s_mov_b64 s[6:7], 0x12000
	v_lshl_add_u64 v[120:121], v[24:25], 0, s[6:7]
	global_load_dwordx4 v[36:39], v[120:121], off nt
	s_mov_b64 s[6:7], 0x1b000
	v_lshl_add_u64 v[120:121], v[24:25], 0, s[6:7]
	global_load_dwordx4 v[40:43], v[120:121], off nt
	s_mov_b64 s[6:7], 0x24000
	v_lshl_add_u64 v[120:121], v[24:25], 0, s[6:7]
	global_load_dwordx4 v[72:75], v[120:121], off nt
	s_mov_b64 s[6:7], 0x2d000
	v_lshl_add_u64 v[120:121], v[24:25], 0, s[6:7]
	global_load_dwordx4 v[76:79], v[120:121], off nt
	s_mov_b64 s[6:7], 0x36000
	v_lshl_add_u64 v[120:121], v[24:25], 0, s[6:7]
	global_load_dwordx4 v[80:83], v[120:121], off nt
	s_mov_b64 s[6:7], 0x3f000
	v_lshl_add_u64 v[120:121], v[24:25], 0, s[6:7]
	global_load_dwordx4 v[84:87], v[120:121], off nt
	s_mov_b64 s[6:7], 0x48000
	v_lshl_add_u64 v[120:121], v[24:25], 0, s[6:7]
	global_load_dwordx4 v[88:91], v[120:121], off nt
	s_mov_b64 s[6:7], 0x51000
	v_lshl_add_u64 v[120:121], v[24:25], 0, s[6:7]
	global_load_dwordx4 v[92:95], v[120:121], off nt
	s_mov_b64 s[6:7], 0x5a000
	v_lshl_add_u64 v[120:121], v[24:25], 0, s[6:7]
	global_load_dwordx4 v[96:99], v[120:121], off nt
	s_mov_b64 s[6:7], 0x63000
	v_lshl_add_u64 v[120:121], v[24:25], 0, s[6:7]
	global_load_dwordx4 v[100:103], v[120:121], off nt
	s_mov_b64 s[6:7], 0x6c000
	v_lshl_add_u64 v[120:121], v[24:25], 0, s[6:7]
	global_load_dwordx4 v[104:107], v[120:121], off nt
	s_mov_b64 s[6:7], 0x75000
	v_lshl_add_u64 v[120:121], v[24:25], 0, s[6:7]
	global_load_dwordx4 v[108:111], v[120:121], off nt
	s_mov_b64 s[6:7], 0x7e000
	v_lshl_add_u64 v[120:121], v[24:25], 0, s[6:7]
	global_load_dwordx4 v[112:115], v[120:121], off nt
	s_mov_b64 s[6:7], 0x87000
	v_lshl_add_u64 v[120:121], v[24:25], 0, s[6:7]
	global_load_dwordx4 v[116:119], v[120:121], off nt
	v_mov_b32_e32 v60, s12
	ds_read_b128 v[44:47], v60
	ds_read_b128 v[48:51], v60 offset:4096
	ds_read_b128 v[52:55], v60 offset:8192
	ds_read_b128 v[56:59], v60 offset:12288
	ds_read_b128 v[60:63], v60 offset:16384
	s_add_i32 s12, s12, 16
	s_waitcnt lgkmcnt(0)
	v_mov_b32_e32 v64, v47
	v_mov_b32_e32 v66, v51
	v_mov_b32_e32 v68, v55
	v_mov_b32_e32 v70, v59
	s_waitcnt vmcnt(12)
	v_pk_fma_f32 v[2:3], v[30:31], v[44:45], v[2:3] op_sel_hi:[1,0,1]
	v_pk_fma_f32 v[0:1], v[28:29], v[44:45], v[0:1] op_sel_hi:[1,0,1]
	v_pk_fma_f32 v[6:7], v[30:31], v[48:49], v[6:7] op_sel_hi:[1,0,1]
	v_pk_fma_f32 v[4:5], v[28:29], v[48:49], v[4:5] op_sel_hi:[1,0,1]
	v_pk_fma_f32 v[10:11], v[30:31], v[52:53], v[10:11] op_sel_hi:[1,0,1]
	v_pk_fma_f32 v[8:9], v[28:29], v[52:53], v[8:9] op_sel_hi:[1,0,1]
	v_pk_fma_f32 v[14:15], v[30:31], v[56:57], v[14:15] op_sel_hi:[1,0,1]
	v_pk_fma_f32 v[12:13], v[28:29], v[56:57], v[12:13] op_sel_hi:[1,0,1]
	v_pk_fma_f32 v[18:19], v[30:31], v[60:61], v[18:19] op_sel_hi:[1,0,1]
	v_pk_fma_f32 v[16:17], v[28:29], v[60:61], v[16:17] op_sel_hi:[1,0,1]
	v_mov_b32_e32 v28, v63
	v_pk_fma_f32 v[0:1], v[32:33], v[44:45], v[0:1] op_sel:[0,1,0]
	v_pk_fma_f32 v[2:3], v[34:35], v[44:45], v[2:3] op_sel:[0,1,0]
	v_pk_fma_f32 v[4:5], v[32:33], v[48:49], v[4:5] op_sel:[0,1,0]
	v_pk_fma_f32 v[6:7], v[34:35], v[48:49], v[6:7] op_sel:[0,1,0]
	v_pk_fma_f32 v[8:9], v[32:33], v[52:53], v[8:9] op_sel:[0,1,0]
	v_pk_fma_f32 v[10:11], v[34:35], v[52:53], v[10:11] op_sel:[0,1,0]
	v_pk_fma_f32 v[12:13], v[32:33], v[56:57], v[12:13] op_sel:[0,1,0]
	v_pk_fma_f32 v[14:15], v[34:35], v[56:57], v[14:15] op_sel:[0,1,0]
	v_pk_fma_f32 v[16:17], v[32:33], v[60:61], v[16:17] op_sel:[0,1,0]
	v_pk_fma_f32 v[18:19], v[34:35], v[60:61], v[18:19] op_sel:[0,1,0]
	v_pk_fma_f32 v[2:3], v[38:39], v[46:47], v[2:3] op_sel_hi:[1,0,1]
	v_pk_fma_f32 v[0:1], v[36:37], v[46:47], v[0:1] op_sel_hi:[1,0,1]
	v_pk_fma_f32 v[6:7], v[38:39], v[50:51], v[6:7] op_sel_hi:[1,0,1]
	v_pk_fma_f32 v[4:5], v[36:37], v[50:51], v[4:5] op_sel_hi:[1,0,1]
	v_pk_fma_f32 v[10:11], v[38:39], v[54:55], v[10:11] op_sel_hi:[1,0,1]
	v_pk_fma_f32 v[8:9], v[36:37], v[54:55], v[8:9] op_sel_hi:[1,0,1]
	v_pk_fma_f32 v[14:15], v[38:39], v[58:59], v[14:15] op_sel_hi:[1,0,1]
	v_pk_fma_f32 v[12:13], v[36:37], v[58:59], v[12:13] op_sel_hi:[1,0,1]
	v_pk_fma_f32 v[18:19], v[38:39], v[62:63], v[18:19] op_sel_hi:[1,0,1]
	v_pk_fma_f32 v[16:17], v[36:37], v[62:63], v[16:17] op_sel_hi:[1,0,1]
	v_pk_fma_f32 v[2:3], v[42:43], v[64:65], v[2:3] op_sel_hi:[1,0,1]
	v_pk_fma_f32 v[0:1], v[40:41], v[64:65], v[0:1] op_sel_hi:[1,0,1]
	v_pk_fma_f32 v[6:7], v[42:43], v[66:67], v[6:7] op_sel_hi:[1,0,1]
	v_pk_fma_f32 v[4:5], v[40:41], v[66:67], v[4:5] op_sel_hi:[1,0,1]
	v_pk_fma_f32 v[10:11], v[42:43], v[68:69], v[10:11] op_sel_hi:[1,0,1]
	v_pk_fma_f32 v[8:9], v[40:41], v[68:69], v[8:9] op_sel_hi:[1,0,1]
	v_pk_fma_f32 v[14:15], v[42:43], v[70:71], v[14:15] op_sel_hi:[1,0,1]
	v_pk_fma_f32 v[12:13], v[40:41], v[70:71], v[12:13] op_sel_hi:[1,0,1]
	v_pk_fma_f32 v[18:19], v[42:43], v[28:29], v[18:19] op_sel_hi:[1,0,1]
	v_pk_fma_f32 v[16:17], v[40:41], v[28:29], v[16:17] op_sel_hi:[1,0,1]
	v_mov_b32_e32 v60, s12
	ds_read_b128 v[44:47], v60
	ds_read_b128 v[48:51], v60 offset:4096
	ds_read_b128 v[52:55], v60 offset:8192
	ds_read_b128 v[56:59], v60 offset:12288
	ds_read_b128 v[60:63], v60 offset:16384
	s_add_i32 s12, s12, 16
	s_waitcnt lgkmcnt(0)
; __global__ void __launch_bounds__(512) mk_fwd(Params P) {
;     ...
; #pragma unroll 4
;                 for (int kk = 0; kk < 16; ++kk) { const int k = kbase + kk; const f32x4 w = __builtin_nontemporal_load((const f32x4*)(W + (size_t)k * NMOD));
; #pragma unroll
;                     for (int r = 0; r < 5; ++r) a[r] += w * cond[r * 1024 + k]; }
	v_mov_b32_e32 v64, v47
	v_mov_b32_e32 v66, v51
	v_mov_b32_e32 v68, v55
	v_mov_b32_e32 v70, v59
	s_waitcnt vmcnt(8)
	v_pk_fma_f32 v[2:3], v[74:75], v[44:45], v[2:3] op_sel_hi:[1,0,1]
	v_pk_fma_f32 v[0:1], v[72:73], v[44:45], v[0:1] op_sel_hi:[1,0,1]
	v_pk_fma_f32 v[6:7], v[74:75], v[48:49], v[6:7] op_sel_hi:[1,0,1]
	v_pk_fma_f32 v[4:5], v[72:73], v[48:49], v[4:5] op_sel_hi:[1,0,1]
	v_pk_fma_f32 v[10:11], v[74:75], v[52:53], v[10:11] op_sel_hi:[1,0,1]
	v_pk_fma_f32 v[8:9], v[72:73], v[52:53], v[8:9] op_sel_hi:[1,0,1]
	v_pk_fma_f32 v[14:15], v[74:75], v[56:57], v[14:15] op_sel_hi:[1,0,1]
	v_pk_fma_f32 v[12:13], v[72:73], v[56:57], v[12:13] op_sel_hi:[1,0,1]
	v_pk_fma_f32 v[18:19], v[74:75], v[60:61], v[18:19] op_sel_hi:[1,0,1]
	v_pk_fma_f32 v[16:17], v[72:73], v[60:61], v[16:17] op_sel_hi:[1,0,1]
	v_mov_b32_e32 v72, v63
	v_pk_fma_f32 v[0:1], v[76:77], v[44:45], v[0:1] op_sel:[0,1,0]
	v_pk_fma_f32 v[2:3], v[78:79], v[44:45], v[2:3] op_sel:[0,1,0]
	v_pk_fma_f32 v[4:5], v[76:77], v[48:49], v[4:5] op_sel:[0,1,0]
	v_pk_fma_f32 v[6:7], v[78:79], v[48:49], v[6:7] op_sel:[0,1,0]
	v_pk_fma_f32 v[8:9], v[76:77], v[52:53], v[8:9] op_sel:[0,1,0]
	v_pk_fma_f32 v[10:11], v[78:79], v[52:53], v[10:11] op_sel:[0,1,0]
	v_pk_fma_f32 v[12:13], v[76:77], v[56:57], v[12:13] op_sel:[0,1,0]
	v_pk_fma_f32 v[14:15], v[78:79], v[56:57], v[14:15] op_sel:[0,1,0]
	v_pk_fma_f32 v[16:17], v[76:77], v[60:61], v[16:17] op_sel:[0,1,0]
	v_pk_fma_f32 v[18:19], v[78:79], v[60:61], v[18:19] op_sel:[0,1,0]
	v_pk_fma_f32 v[2:3], v[82:83], v[46:47], v[2:3] op_sel_hi:[1,0,1]
	v_pk_fma_f32 v[0:1], v[80:81], v[46:47], v[0:1] op_sel_hi:[1,0,1]
	v_pk_fma_f32 v[6:7], v[82:83], v[50:51], v[6:7] op_sel_hi:[1,0,1]
	v_pk_fma_f32 v[4:5], v[80:81], v[50:51], v[4:5] op_sel_hi:[1,0,1]
	v_pk_fma_f32 v[10:11], v[82:83], v[54:55], v[10:11] op_sel_hi:[1,0,1]
	v_pk_fma_f32 v[8:9], v[80:81], v[54:55], v[8:9] op_sel_hi:[1,0,1]
	v_pk_fma_f32 v[14:15], v[82:83], v[58:59], v[14:15] op_sel_hi:[1,0,1]
	v_pk_fma_f32 v[12:13], v[80:81], v[58:59], v[12:13] op_sel_hi:[1,0,1]
	v_pk_fma_f32 v[18:19], v[82:83], v[62:63], v[18:19] op_sel_hi:[1,0,1]
	v_pk_fma_f32 v[16:17], v[80:81], v[62:63], v[16:17] op_sel_hi:[1,0,1]
	v_pk_fma_f32 v[2:3], v[86:87], v[64:65], v[2:3] op_sel_hi:[1,0,1]
	v_pk_fma_f32 v[0:1], v[84:85], v[64:65], v[0:1] op_sel_hi:[1,0,1]
	v_pk_fma_f32 v[6:7], v[86:87], v[66:67], v[6:7] op_sel_hi:[1,0,1]
	v_pk_fma_f32 v[4:5], v[84:85], v[66:67], v[4:5] op_sel_hi:[1,0,1]
	v_pk_fma_f32 v[10:11], v[86:87], v[68:69], v[10:11] op_sel_hi:[1,0,1]
	v_pk_fma_f32 v[8:9], v[84:85], v[68:69], v[8:9] op_sel_hi:[1,0,1]
	v_pk_fma_f32 v[14:15], v[86:87], v[70:71], v[14:15] op_sel_hi:[1,0,1]
	v_pk_fma_f32 v[12:13], v[84:85], v[70:71], v[12:13] op_sel_hi:[1,0,1]
	v_pk_fma_f32 v[18:19], v[86:87], v[72:73], v[18:19] op_sel_hi:[1,0,1]
	v_pk_fma_f32 v[16:17], v[84:85], v[72:73], v[16:17] op_sel_hi:[1,0,1]
	v_mov_b32_e32 v60, s12
	ds_read_b128 v[44:47], v60
	ds_read_b128 v[48:51], v60 offset:4096
	ds_read_b128 v[52:55], v60 offset:8192
	ds_read_b128 v[56:59], v60 offset:12288
	ds_read_b128 v[60:63], v60 offset:16384
	s_add_i32 s12, s12, 16
	s_waitcnt lgkmcnt(0)
	v_mov_b32_e32 v64, v47
	v_mov_b32_e32 v66, v51
	v_mov_b32_e32 v68, v55
	v_mov_b32_e32 v70, v59
	s_waitcnt vmcnt(4)
	v_pk_fma_f32 v[2:3], v[90:91], v[44:45], v[2:3] op_sel_hi:[1,0,1]
	v_pk_fma_f32 v[0:1], v[88:89], v[44:45], v[0:1] op_sel_hi:[1,0,1]
	v_pk_fma_f32 v[6:7], v[90:91], v[48:49], v[6:7] op_sel_hi:[1,0,1]
	v_pk_fma_f32 v[4:5], v[88:89], v[48:49], v[4:5] op_sel_hi:[1,0,1]
	v_pk_fma_f32 v[10:11], v[90:91], v[52:53], v[10:11] op_sel_hi:[1,0,1]
	v_pk_fma_f32 v[8:9], v[88:89], v[52:53], v[8:9] op_sel_hi:[1,0,1]
	v_pk_fma_f32 v[14:15], v[90:91], v[56:57], v[14:15] op_sel_hi:[1,0,1]
	v_pk_fma_f32 v[12:13], v[88:89], v[56:57], v[12:13] op_sel_hi:[1,0,1]
	v_pk_fma_f32 v[18:19], v[90:91], v[60:61], v[18:19] op_sel_hi:[1,0,1]
	v_pk_fma_f32 v[16:17], v[88:89], v[60:61], v[16:17] op_sel_hi:[1,0,1]
	v_mov_b32_e32 v88, v63
	v_pk_fma_f32 v[0:1], v[92:93], v[44:45], v[0:1] op_sel:[0,1,0]
	v_pk_fma_f32 v[2:3], v[94:95], v[44:45], v[2:3] op_sel:[0,1,0]
	v_pk_fma_f32 v[4:5], v[92:93], v[48:49], v[4:5] op_sel:[0,1,0]
	v_pk_fma_f32 v[6:7], v[94:95], v[48:49], v[6:7] op_sel:[0,1,0]
	v_pk_fma_f32 v[8:9], v[92:93], v[52:53], v[8:9] op_sel:[0,1,0]
	v_pk_fma_f32 v[10:11], v[94:95], v[52:53], v[10:11] op_sel:[0,1,0]
	v_pk_fma_f32 v[12:13], v[92:93], v[56:57], v[12:13] op_sel:[0,1,0]
	v_pk_fma_f32 v[14:15], v[94:95], v[56:57], v[14:15] op_sel:[0,1,0]
	v_pk_fma_f32 v[16:17], v[92:93], v[60:61], v[16:17] op_sel:[0,1,0]
	v_pk_fma_f32 v[18:19], v[94:95], v[60:61], v[18:19] op_sel:[0,1,0]
	v_pk_fma_f32 v[2:3], v[98:99], v[46:47], v[2:3] op_sel_hi:[1,0,1]
	v_pk_fma_f32 v[0:1], v[96:97], v[46:47], v[0:1] op_sel_hi:[1,0,1]
	v_pk_fma_f32 v[6:7], v[98:99], v[50:51], v[6:7] op_sel_hi:[1,0,1]
	v_pk_fma_f32 v[4:5], v[96:97], v[50:51], v[4:5] op_sel_hi:[1,0,1]
	v_pk_fma_f32 v[10:11], v[98:99], v[54:55], v[10:11] op_sel_hi:[1,0,1]
	v_pk_fma_f32 v[8:9], v[96:97], v[54:55], v[8:9] op_sel_hi:[1,0,1]
	v_pk_fma_f32 v[14:15], v[98:99], v[58:59], v[14:15] op_sel_hi:[1,0,1]
	v_pk_fma_f32 v[12:13], v[96:97], v[58:59], v[12:13] op_sel_hi:[1,0,1]
	v_pk_fma_f32 v[18:19], v[98:99], v[62:63], v[18:19] op_sel_hi:[1,0,1]
	v_pk_fma_f32 v[16:17], v[96:97], v[62:63], v[16:17] op_sel_hi:[1,0,1]
	v_pk_fma_f32 v[2:3], v[102:103], v[64:65], v[2:3] op_sel_hi:[1,0,1]
	v_pk_fma_f32 v[0:1], v[100:101], v[64:65], v[0:1] op_sel_hi:[1,0,1]
	v_pk_fma_f32 v[6:7], v[102:103], v[66:67], v[6:7] op_sel_hi:[1,0,1]
	v_pk_fma_f32 v[4:5], v[100:101], v[66:67], v[4:5] op_sel_hi:[1,0,1]
	v_pk_fma_f32 v[10:11], v[102:103], v[68:69], v[10:11] op_sel_hi:[1,0,1]
	v_pk_fma_f32 v[8:9], v[100:101], v[68:69], v[8:9] op_sel_hi:[1,0,1]
	v_pk_fma_f32 v[14:15], v[102:103], v[70:71], v[14:15] op_sel_hi:[1,0,1]
	v_pk_fma_f32 v[12:13], v[100:101], v[70:71], v[12:13] op_sel_hi:[1,0,1]
	v_pk_fma_f32 v[18:19], v[102:103], v[88:89], v[18:19] op_sel_hi:[1,0,1]
	v_pk_fma_f32 v[16:17], v[100:101], v[88:89], v[16:17] op_sel_hi:[1,0,1]
	v_mov_b32_e32 v60, s12
	ds_read_b128 v[44:47], v60
	ds_read_b128 v[48:51], v60 offset:4096
	ds_read_b128 v[52:55], v60 offset:8192
	ds_read_b128 v[56:59], v60 offset:12288
	ds_read_b128 v[60:63], v60 offset:16384
	s_add_i32 s12, s12, 16
	s_waitcnt lgkmcnt(0)
; __global__ void __launch_bounds__(512) mk_fwd(Params P) {
;     ...
; #pragma unroll 4
;                 for (int kk = 0; kk < 16; ++kk) { const int k = kbase + kk; const f32x4 w = __builtin_nontemporal_load((const f32x4*)(W + (size_t)k * NMOD));
; #pragma unroll
;                     for (int r = 0; r < 5; ++r) a[r] += w * cond[r * 1024 + k]; }
; #pragma unroll
;                 for (int r = 0; r < 5; ++r) *(f32x4*)(red + (wave * 5 + r) * 256 + lane * 4) = a[r];
;                 __syncthreads();
;                 for (int o = tid; o < 1280; o += 512) { const int r = o >> 8, cc = o & 255; float sum = 0.f;
; #pragma unroll
;                     for (int w = 0; w < 8; ++w) sum += red[(w * 5 + r) * 256 + cc];
;                     MODP[(size_t)((ks * 4 + ll) * 5 + r) * NMOD + cgp * 256 + cc] = sum; }
	v_mov_b32_e32 v64, v47
	v_mov_b32_e32 v66, v51
	v_mov_b32_e32 v68, v55
	v_mov_b32_e32 v70, v59
	s_waitcnt vmcnt(0)
	v_pk_fma_f32 v[2:3], v[106:107], v[44:45], v[2:3] op_sel_hi:[1,0,1]
	v_pk_fma_f32 v[0:1], v[104:105], v[44:45], v[0:1] op_sel_hi:[1,0,1]
	v_pk_fma_f32 v[6:7], v[106:107], v[48:49], v[6:7] op_sel_hi:[1,0,1]
	v_pk_fma_f32 v[4:5], v[104:105], v[48:49], v[4:5] op_sel_hi:[1,0,1]
	v_pk_fma_f32 v[10:11], v[106:107], v[52:53], v[10:11] op_sel_hi:[1,0,1]
	v_pk_fma_f32 v[8:9], v[104:105], v[52:53], v[8:9] op_sel_hi:[1,0,1]
	v_pk_fma_f32 v[14:15], v[106:107], v[56:57], v[14:15] op_sel_hi:[1,0,1]
	v_pk_fma_f32 v[12:13], v[104:105], v[56:57], v[12:13] op_sel_hi:[1,0,1]
	v_pk_fma_f32 v[18:19], v[106:107], v[60:61], v[18:19] op_sel_hi:[1,0,1]
	v_pk_fma_f32 v[16:17], v[104:105], v[60:61], v[16:17] op_sel_hi:[1,0,1]
	v_mov_b32_e32 v104, v63
	v_pk_fma_f32 v[0:1], v[108:109], v[44:45], v[0:1] op_sel:[0,1,0]
	v_pk_fma_f32 v[2:3], v[110:111], v[44:45], v[2:3] op_sel:[0,1,0]
	v_pk_fma_f32 v[4:5], v[108:109], v[48:49], v[4:5] op_sel:[0,1,0]
	v_pk_fma_f32 v[6:7], v[110:111], v[48:49], v[6:7] op_sel:[0,1,0]
	v_pk_fma_f32 v[8:9], v[108:109], v[52:53], v[8:9] op_sel:[0,1,0]
	v_pk_fma_f32 v[10:11], v[110:111], v[52:53], v[10:11] op_sel:[0,1,0]
	v_pk_fma_f32 v[12:13], v[108:109], v[56:57], v[12:13] op_sel:[0,1,0]
	v_pk_fma_f32 v[14:15], v[110:111], v[56:57], v[14:15] op_sel:[0,1,0]
	v_pk_fma_f32 v[16:17], v[108:109], v[60:61], v[16:17] op_sel:[0,1,0]
	v_pk_fma_f32 v[18:19], v[110:111], v[60:61], v[18:19] op_sel:[0,1,0]
	v_pk_fma_f32 v[2:3], v[114:115], v[46:47], v[2:3] op_sel_hi:[1,0,1]
	v_pk_fma_f32 v[0:1], v[112:113], v[46:47], v[0:1] op_sel_hi:[1,0,1]
	v_pk_fma_f32 v[6:7], v[114:115], v[50:51], v[6:7] op_sel_hi:[1,0,1]
	v_pk_fma_f32 v[4:5], v[112:113], v[50:51], v[4:5] op_sel_hi:[1,0,1]
	v_pk_fma_f32 v[10:11], v[114:115], v[54:55], v[10:11] op_sel_hi:[1,0,1]
	v_pk_fma_f32 v[8:9], v[112:113], v[54:55], v[8:9] op_sel_hi:[1,0,1]
	v_pk_fma_f32 v[14:15], v[114:115], v[58:59], v[14:15] op_sel_hi:[1,0,1]
	v_pk_fma_f32 v[12:13], v[112:113], v[58:59], v[12:13] op_sel_hi:[1,0,1]
	v_pk_fma_f32 v[18:19], v[114:115], v[62:63], v[18:19] op_sel_hi:[1,0,1]
	v_pk_fma_f32 v[16:17], v[112:113], v[62:63], v[16:17] op_sel_hi:[1,0,1]
	v_pk_fma_f32 v[2:3], v[118:119], v[64:65], v[2:3] op_sel_hi:[1,0,1]
	v_pk_fma_f32 v[0:1], v[116:117], v[64:65], v[0:1] op_sel_hi:[1,0,1]
	v_pk_fma_f32 v[6:7], v[118:119], v[66:67], v[6:7] op_sel_hi:[1,0,1]
	v_pk_fma_f32 v[4:5], v[116:117], v[66:67], v[4:5] op_sel_hi:[1,0,1]
	v_pk_fma_f32 v[10:11], v[118:119], v[68:69], v[10:11] op_sel_hi:[1,0,1]
	v_pk_fma_f32 v[8:9], v[116:117], v[68:69], v[8:9] op_sel_hi:[1,0,1]
	v_pk_fma_f32 v[14:15], v[118:119], v[70:71], v[14:15] op_sel_hi:[1,0,1]
	v_pk_fma_f32 v[12:13], v[116:117], v[70:71], v[12:13] op_sel_hi:[1,0,1]
	v_pk_fma_f32 v[18:19], v[118:119], v[104:105], v[18:19] op_sel_hi:[1,0,1]
	v_pk_fma_f32 v[16:17], v[116:117], v[104:105], v[16:17] op_sel_hi:[1,0,1]
	ds_write_b128 v27, v[0:3] offset:20480
	ds_write_b128 v27, v[4:7] offset:21504
	ds_write_b128 v27, v[8:11] offset:22528
	ds_write_b128 v27, v[12:15] offset:23552
	ds_write_b128 v27, v[16:19] offset:24576
	s_waitcnt lgkmcnt(0)
	s_barrier
	s_and_saveexec_b64 s[8:9], vcc
	s_cbranch_execz .LBB0_596
	s_and_b32 s6, s2, 7
	s_lshl_b32 s6, s6, 2
	s_add_i32 s11, s6, s11
	s_mul_i32 s11, s11, 5
	v_lshl_add_u64 v[0:1], s[0:1], 2, v[20:21]
	s_mov_b64 s[0:1], 0
	v_mov_b32_e32 v2, v146
